# attention K/V staging by direct HBM->LDS loads (global_load_lds, source-side swizzle), issued at segment start, one vmcnt(0) before the closing barrier
# speedup vs baseline: 1.0112x; 1.0112x over previous
; DI int v_st(int k, int c) { const int kk = (k & ~0xC) | ((k & 4) << 1) | ((k & 8) >> 1); return ((kk >> 3) * 4 + (c >> 5)) * 512 + ((kk & 7) * 32 + (c & 31)) * 2; }
; DI int v_rd_base(int lane) { return ((lane & 3) << 3) | (((lane >> 2) & 3) << 6) | (((lane >> 4) & 1) << 5) | (((lane >> 5) & 1) << 8); }
; #define SLOAD(i, k0) do { sr_[i].vs0 = *(const bf16x8*)(&Vh[(long)((k0) + sr) * LDA_ + sc]); sr_[i].vs1 = *(const bf16x8*)(&Vh[(long)((k0) + 32 + sr) * LDA_ + sc]); \
;     sr_[i].ks0 = *(const bf16x8*)(&Kh[(long)((k0) + sr) * LDA_ + sc]); sr_[i].ks1 = *(const bf16x8*)(&Kh[(long)((k0) + 32 + sr) * LDA_ + sc]); } while (0)
; #define SWRITE(b, i) do { *(bf16x8*)(V_lds + (b) * SHM_V + vst0) = sr_[i].vs0;          \
;     *(bf16x8*)(V_lds + (b) * SHM_V + vst1) = sr_[i].vs1; int kc = sc * 2;               \
;     *(bf16x8*)(K_lds + (b) * SHM_K + KSWZ(sr, kc)) = sr_[i].ks0;                       \
;     *(bf16x8*)(K_lds + (b) * SHM_K + KSWZ(32 + sr, kc)) = sr_[i].ks1; } while (0)
; DI void attn_unit(const bf16_t* __restrict__ Qb, const bf16_t* __restrict__ Kh, const bf16_t* __restrict__ Vh, bf16_t* __restrict__ Ob, const float* __restrict__ onw, int seq, char* lds) {
;     int tid_ = threadIdx.x; asm volatile("" : "+v"(tid_));
;     const int tid = tid_, wid = tid >> 6, lane = tid & 63, r32 = lane & 31, hi = lane >> 5;
;     char* V_lds = lds; char* K_lds = lds + 2 * SHM_V;
;     float* wsf = (float*)(lds + 2 * SHM_V + 2 * SHM_K) + wid * 64; float* li_l = wsf; float* al_l = wsf + 32;
;     float m_reg = 0.f, l_reg = 0; f32x16 o[4]; bf16x8 qr[8];
; #pragma unroll
;     for (int d = 0; d < 4; ++d)
; #pragma unroll
;         for (int i = 0; i < 16; ++i) o[d][i] = 0.f;
;     const bf16_t* Qw = Qb + (long)((wid & 3) * 32 + r32) * LDA_ + (wid >> 2) * 128 + hi * 8;
; #pragma unroll
;     for (int d0 = 0; d0 < 8; ++d0) qr[d0] = *(const bf16x8*)(Qw + d0 * 16);
;     const int sr = tid >> 4, sc = (tid & 15) * 8, vst0 = v_st(sr, sc), vst1 = v_st(32 + sr, sc);
;     const int vb0 = (int)(uintptr_t)V_lds + v_rd_base(lane);
;     struct { bf16x8 vs0, vs1, ks0, ks1; } sr_[1];
;     ...
;     f32x16 pA0, pA1, pB0, pB1; float alA, alB; bf16x8 pa0, pa1, pa2, pa3; const int NT = seq / 64;
;     constexpr int SE = 0, SO = 0;
;     SLOAD(SE, 0); asm volatile("s_waitcnt vmcnt(0)" ::: "memory"); SWRITE(0, SE); __syncthreads();
.LBB0_579:
	s_and_b32 s12, s14, 1
	s_lshl_b32 s2, s15, 7
	s_add_u32 s2, s68, s2
	s_addc_u32 s3, s69, 0
	s_lshl_b64 s[66:67], s[2:3], 10
	s_lshl_b64 s[2:3], s[2:3], 11
	s_add_u32 s2, s30, s2
	s_addc_u32 s3, s31, s3
	s_lshl_b32 s72, s12, 8
	s_lshl_b32 s12, s12, 9
	s_add_u32 s2, s2, s12
	s_waitcnt vmcnt(0)
	v_mov_b32_e32 v80, v192
	s_addc_u32 s3, s3, 0
	s_lshl_b64 s[14:15], s[68:69], 11
	s_add_u32 s12, s30, s14
	v_ashrrev_i32_e32 v48, 4, v80
	v_lshlrev_b32_e32 v20, 3, v80
	v_add_u32_e32 v16, 32, v48
	s_addc_u32 s15, s31, s15
	v_and_b32_e32 v0, 0x78, v20
	v_ashrrev_i32_e32 v49, 31, v48
	v_ashrrev_i32_e32 v17, 31, v16
	s_add_u32 s14, s12, s72
	v_lshlrev_b32_e32 v21, 1, v0
	v_lshlrev_b64 v[0:1], 11, v[48:49]
	v_lshlrev_b64 v[4:5], 11, v[16:17]
	s_addc_u32 s15, s15, 0
	v_or_b32_e32 v0, v0, v21
	v_or_b32_e32 v4, v4, v21
	v_lshl_add_u64 v[50:51], s[14:15], 0, v[0:1]
	v_lshl_add_u64 v[12:13], s[14:15], 0, v[4:5]
	s_add_u32 s98, s14, 0x20400
	s_addc_u32 s99, s15, 0
	v_readfirstlane_b32 s100, v80
	v_and_b32_e32 v250, 63, v80
	v_lshrrev_b32_e32 v251, 6, v80
	v_lshrrev_b32_e32 v252, 4, v250
	v_and_b32_e32 v253, 1, v251
	v_lshl_add_u32 v253, v253, 2, v252
	v_and_b32_e32 v246, 15, v250
	v_xor_b32_e32 v246, v246, v253
	v_lshlrev_b32_e32 v246, 4, v246
	v_lshl_add_u32 v252, v251, 2, v252
	v_lshl_add_u32 v246, v252, 11, v246
	v_add_u32_e32 v246, 0x20000, v246
	v_add_u32_e32 v247, 0x10000, v246
	v_bfe_u32 v252, v250, 2, 3
	v_and_b32_e32 v253, 3, v252
	v_lshrrev_b32_e32 v252, 2, v252
	v_lshl_add_u32 v253, v252, 3, v253
	v_bfe_u32 v252, v251, 1, 1
	v_lshl_add_u32 v253, v252, 2, v253
	v_bfe_u32 v252, v251, 2, 1
	v_lshl_add_u32 v253, v252, 4, v253
	v_lshlrev_b32_e32 v248, 11, v253
	v_and_b32_e32 v252, 1, v251
	v_lshlrev_b32_e32 v252, 1, v252
	v_lshrrev_b32_e32 v253, 5, v250
	v_add_u32_e32 v252, v252, v253
	v_and_b32_e32 v253, 3, v250
	v_lshl_add_u32 v252, v252, 2, v253
	v_lshl_add_u32 v248, v252, 4, v248
	v_add_u32_e32 v248, 0x200, v248
	v_add_u32_e32 v249, 0x10000, v248
	s_lshl_b32 s100, s100, 4
	global_load_dwordx4 v[0:3], v[50:51], off offset:1536
	global_load_dwordx4 v[4:7], v[12:13], off offset:1536
	global_load_dwordx4 v[8:11], v[50:51], off offset:1024
	s_nop 0
	global_load_dwordx4 v[12:15], v[12:13], off offset:1024
	v_lshrrev_b32_e32 v17, 1, v80
	v_and_b32_e32 v155, 31, v80
	v_and_b32_e32 v170, 0x60, v17
	v_or_b32_e32 v17, v170, v155
	v_lshlrev_b32_e32 v184, 11, v17
	v_ashrrev_i32_e32 v17, 1, v80
	v_and_b32_e32 v148, 0xffffff80, v17
	v_bfe_u32 v151, v80, 5, 1
	v_lshl_add_u64 v[18:19], s[2:3], 0, v[184:185]
	v_ashrrev_i32_e32 v149, 31, v148
	v_lshl_add_u64 v[18:19], v[148:149], 1, v[18:19]
	v_lshlrev_b32_e32 v184, 4, v151
	v_lshl_add_u64 v[18:19], v[18:19], 0, v[184:185]
	global_load_dwordx4 v[140:143], v[18:19], off
	global_load_dwordx4 v[136:139], v[18:19], off offset:32
	global_load_dwordx4 v[132:135], v[18:19], off offset:64
	global_load_dwordx4 v[128:131], v[18:19], off offset:96
	global_load_dwordx4 v[124:127], v[18:19], off offset:128
	global_load_dwordx4 v[120:123], v[18:19], off offset:160
	global_load_dwordx4 v[116:119], v[18:19], off offset:192
	global_load_dwordx4 v[112:115], v[18:19], off offset:224
	v_and_b32_e32 v22, 0xfffff0, v48
	v_lshlrev_b32_e32 v23, 1, v48
	v_lshrrev_b32_e32 v24, 1, v48
	v_and_b32_e32 v25, 3, v48
	v_and_or_b32 v22, v23, 8, v22
	v_and_or_b32 v23, v24, 4, v25
	v_and_b32_e32 v24, 0xfffff0, v16
	v_lshlrev_b32_e32 v25, 1, v16
	v_and_b32_e32 v17, 0x70, v80
	v_bfe_u32 v20, v20, 5, 2
	v_lshlrev_b32_e32 v26, 8, v48
	v_lshlrev_b32_e32 v16, 8, v16
	v_lshrrev_b32_e32 v22, 1, v22
	v_and_or_b32 v24, v25, 8, v24
	v_and_b32_e32 v27, 48, v21
	v_bitop3_b32 v25, v21, v26, v17 bitop3:0xde
	v_bitop3_b32 v16, v21, v16, v17 bitop3:0xde
	v_or_b32_e32 v17, v22, v20
	v_lshrrev_b32_e32 v21, 1, v24
	v_lshlrev_b32_e32 v23, 6, v23
	v_add_u32_e32 v205, 0, v16
	v_lshlrev_b32_e32 v16, 9, v17
	v_or_b32_e32 v17, v21, v20
	v_or3_b32 v16, v16, v23, v27
	v_lshlrev_b32_e32 v17, 9, v17
	v_lshlrev_b32_e32 v66, 4, v80
	v_or3_b32 v17, v17, v23, v27
	v_add_u32_e32 v206, 0, v16
	v_add_u32_e32 v204, 0, v25
	v_add_u32_e32 v207, 0, v17
	s_waitcnt vmcnt(0)
	s_mov_b64 s[2:3], 0x20000
	v_and_b32_e32 v81, 63, v80
	s_mov_b32 s12, s13
	s_mov_b32 s14, s13
	s_mov_b32 s15, s13
	s_mov_b32 s16, s13
	s_mov_b32 s17, s13
	s_mov_b32 s18, s13
	s_mov_b32 s19, s13
	s_mov_b32 s20, s13
	s_mov_b32 s21, s13
	s_mov_b32 s22, s13
	s_waitcnt vmcnt(11)
	ds_write_b128 v206, v[0:3]
	s_waitcnt vmcnt(10)
	ds_write_b128 v207, v[4:7]
	s_waitcnt vmcnt(9)
	ds_write_b128 v204, v[8:11] offset:32768
	s_waitcnt vmcnt(8)
	ds_write_b128 v205, v[12:15] offset:32768
	v_lshlrev_b32_e32 v12, 8, v155
	v_and_b32_e32 v13, 0x70, v66
	v_bitop3_b32 v0, v184, v12, v13 bitop3:0xde
	v_add_u32_e32 v183, 0, v0
	s_waitcnt lgkmcnt(0)
	s_barrier
; #define MFMA32(a, b, c) __builtin_amdgcn_mfma_f32_32x32x16_bf16((a), (b), (c), 0, 0, 0)
; #define SLOAD(i, k0) do { sr_[i].vs0 = *(const bf16x8*)(&Vh[(long)((k0) + sr) * LDA_ + sc]); sr_[i].vs1 = *(const bf16x8*)(&Vh[(long)((k0) + 32 + sr) * LDA_ + sc]); \
;     sr_[i].ks0 = *(const bf16x8*)(&Kh[(long)((k0) + sr) * LDA_ + sc]); sr_[i].ks1 = *(const bf16x8*)(&Kh[(long)((k0) + 32 + sr) * LDA_ + sc]); } while (0)
; #define SWRITE(b, i) do { *(bf16x8*)(V_lds + (b) * SHM_V + vst0) = sr_[i].vs0;          \
;     *(bf16x8*)(V_lds + (b) * SHM_V + vst1) = sr_[i].vs1; int kc = sc * 2;               \
;     *(bf16x8*)(K_lds + (b) * SHM_K + KSWZ(sr, kc)) = sr_[i].ks0;                       \
;     *(bf16x8*)(K_lds + (b) * SHM_K + KSWZ(32 + sr, kc)) = sr_[i].ks1; } while (0)
; #define SWAIT() asm volatile("s_waitcnt vmcnt(0)" ::: "memory")
; DI void qkt(f32x16& p0, f32x16& p1, const char* Ks, const bf16x8* qr, float negm, int r32, int hi) {
; #pragma unroll
;     for (int i = 0; i < 16; ++i) { p0[i] = negm; p1[i] = negm; }
; #pragma unroll
;     for (int d0 = 0; d0 < 8; ++d0) { const int cb = (d0 * 16 + hi * 8) * 2;
;         bf16x8 b0 = *(const bf16x8*)(Ks + KSWZ(r32, cb));
;         bf16x8 b1 = *(const bf16x8*)(Ks + KSWZ(32 + r32, cb));
;         p0 = MFMA32(b0, qr[d0], p0);
;         p1 = MFMA32(b1, qr[d0], p1); }
; }
; DI void attn_unit(const bf16_t* __restrict__ Qb, const bf16_t* __restrict__ Kh, const bf16_t* __restrict__ Vh, bf16_t* __restrict__ Ob, const float* __restrict__ onw, int seq, char* lds) {
;     ...
;     qkt(pA0, pA1, K_lds, qr, 0.f, r32, hi); partialSM<true>(pA0, pA1, m_reg, alA);
;     SLOAD(SO, 64);
;     SWAIT(); SWRITE(1, SO); __syncthreads();
	ds_read_b128 v[0:3], v183 offset:32768
	ds_read_b128 v[4:7], v183 offset:40960
	s_waitcnt vmcnt(7) lgkmcnt(1)
	v_mfma_f32_32x32x16_bf16 v[32:47], v[0:3], v[140:143], 0
	v_or_b32_e32 v0, 32, v184
	v_bitop3_b32 v0, v0, v12, v13 bitop3:0xde
	v_add_u32_e32 v208, 0, v0
	v_lshl_add_u64 v[8:9], v[50:51], 0, s[2:3]
	v_lshl_add_u64 v[10:11], v[50:51], 0, s[56:57]
	s_add_i32 s2, 0, 0x10000
	s_cmp_lg_u32 0, -1
	s_waitcnt lgkmcnt(0)
	v_mfma_f32_32x32x16_bf16 v[16:31], v[4:7], v[140:143], 0
	ds_read_b128 v[0:3], v208 offset:32768
	ds_read_b128 v[4:7], v208 offset:40960
	s_mov_b32 s23, s13
	s_mov_b32 s24, s13
	s_mov_b32 s25, s13
	s_mov_b32 s26, s13
	s_mov_b32 s27, s13
	s_cselect_b32 s43, 0, 0
	s_waitcnt vmcnt(6) lgkmcnt(1)
	v_mfma_f32_32x32x16_bf16 v[32:47], v[0:3], v[136:139], v[32:47]
	v_or_b32_e32 v0, 64, v184
	v_bitop3_b32 v0, v0, v12, v13 bitop3:0xde
	v_add_u32_e32 v209, 0, v0
	s_mov_b32 s42, 2
	v_mov_b32_e32 v173, 0
	s_waitcnt lgkmcnt(0)
	v_mfma_f32_32x32x16_bf16 v[16:31], v[4:7], v[136:139], v[16:31]
	ds_read_b128 v[0:3], v209 offset:32768
	ds_read_b128 v[4:7], v209 offset:40960
	s_waitcnt vmcnt(5) lgkmcnt(1)
	v_mfma_f32_32x32x16_bf16 v[32:47], v[0:3], v[132:135], v[32:47]
	v_or_b32_e32 v0, 0x60, v184
	v_bitop3_b32 v0, v0, v12, v13 bitop3:0xde
	v_add_u32_e32 v210, 0, v0
	s_waitcnt lgkmcnt(0)
	v_mfma_f32_32x32x16_bf16 v[16:31], v[4:7], v[132:135], v[16:31]
	ds_read_b128 v[0:3], v210 offset:32768
	ds_read_b128 v[4:7], v210 offset:40960
	s_waitcnt vmcnt(4) lgkmcnt(1)
	v_mfma_f32_32x32x16_bf16 v[32:47], v[0:3], v[128:131], v[32:47]
	v_or_b32_e32 v0, 0x80, v184
	v_bitop3_b32 v0, v0, v12, v13 bitop3:0xde
	v_add_u32_e32 v211, 0, v0
	ds_read_b128 v[0:3], v211 offset:32768
	s_waitcnt lgkmcnt(1)
	v_mfma_f32_32x32x16_bf16 v[16:31], v[4:7], v[128:131], v[16:31]
	ds_read_b128 v[4:7], v211 offset:40960
	global_load_dwordx4 v[50:53], v[8:9], off offset:1536
	global_load_dwordx4 v[54:57], v[10:11], off offset:1536
	global_load_dwordx4 v[58:61], v[8:9], off offset:1024
	global_load_dwordx4 v[62:65], v[10:11], off offset:1024
	v_lshlrev_b32_e32 v8, 3, v81
	v_lshlrev_b32_e32 v10, 1, v80
	s_waitcnt vmcnt(7) lgkmcnt(1)
	v_mfma_f32_32x32x16_bf16 v[32:47], v[0:3], v[124:127], v[32:47]
	v_or_b32_e32 v0, 0xa0, v184
	v_bitop3_b32 v0, v0, v12, v13 bitop3:0xde
	v_add_u32_e32 v212, 0, v0
	ds_read_b128 v[0:3], v212 offset:32768
	s_waitcnt lgkmcnt(1)
	v_mfma_f32_32x32x16_bf16 v[16:31], v[4:7], v[124:127], v[16:31]
	v_and_b32_e32 v4, 0x3fffffc0, v80
	v_lshl_add_u32 v171, v4, 2, s2
	ds_read_b128 v[4:7], v212 offset:40960
	v_cmp_gt_u32_e64 s[2:3], 32, v81
	v_lshl_add_u32 v172, v155, 2, v171
	s_waitcnt vmcnt(6) lgkmcnt(1)
	v_mfma_f32_32x32x16_bf16 v[32:47], v[0:3], v[120:123], v[32:47]
	v_and_b32_e32 v0, 0xc0, v66
	v_and_or_b32 v9, v8, 24, v0
	v_or_b32_e32 v0, 0xc0, v184
	v_bitop3_b32 v0, v0, v12, v13 bitop3:0xde
	v_add_u32_e32 v213, 0, v0
	ds_read_b128 v[0:3], v213 offset:32768
	s_waitcnt lgkmcnt(1)
	v_mfma_f32_32x32x16_bf16 v[16:31], v[4:7], v[120:123], v[16:31]
	v_and_b32_e32 v4, 32, v10
	v_and_b32_e32 v5, 0x100, v8
	v_or3_b32 v82, v9, v4, v5
	ds_read_b128 v[4:7], v213 offset:40960
	v_add_u32_e32 v175, s43, v82
	s_addk_i32 s43, 0x4000
	v_add_u32_e32 v174, s43, v82
	s_waitcnt vmcnt(5) lgkmcnt(1)
	v_mfma_f32_32x32x16_bf16 v[32:47], v[0:3], v[116:119], v[32:47]
	v_or_b32_e32 v0, 0xe0, v184
	v_bitop3_b32 v0, v0, v12, v13 bitop3:0xde
	v_add_u32_e32 v214, 0, v0
	ds_read_b128 v[0:3], v214 offset:32768
	ds_read_b128 v[66:69], v214 offset:40960
	s_waitcnt vmcnt(0)
	s_waitcnt vmcnt(3)
	ds_write_b128 v206, v[50:53] offset:16384
	s_waitcnt vmcnt(2)
	ds_write_b128 v207, v[54:57] offset:16384
	s_waitcnt vmcnt(1)
	ds_write_b128 v204, v[58:61] offset:49152
	s_waitcnt vmcnt(0)
	ds_write_b128 v205, v[62:65] offset:49152
	s_waitcnt lgkmcnt(6)
	v_mfma_f32_32x32x16_bf16 v[16:31], v[4:7], v[116:119], v[16:31]
	s_waitcnt lgkmcnt(0)
	s_barrier
	v_mfma_f32_32x32x16_bf16 v[32:47], v[0:3], v[112:115], v[32:47]
	v_mov_b64_e32 v[0:1], s[12:13]
	v_mov_b64_e32 v[14:15], s[26:27]
	v_mov_b64_e32 v[2:3], s[14:15]
	v_mov_b64_e32 v[4:5], s[16:17]
	v_mov_b64_e32 v[6:7], s[18:19]
	v_mov_b64_e32 v[8:9], s[20:21]
	v_mov_b64_e32 v[10:11], s[22:23]
	v_mfma_f32_32x32x16_bf16 v[16:31], v[66:69], v[112:115], v[16:31]
	s_nop 3
	v_max_f32_e32 v66, v33, v33
	v_max_f32_e32 v67, v32, v32
	v_max_f32_e32 v66, v67, v66
	v_max3_f32 v66, v66, v34, v35
	v_max3_f32 v66, v66, v36, v37
	v_max3_f32 v66, v66, v38, v39
	v_max3_f32 v66, v66, v40, v41
	v_max3_f32 v66, v66, v42, v43
	v_max3_f32 v66, v66, v44, v45
	v_max3_f32 v66, v66, v46, v47
	v_max3_f32 v66, v66, v16, v17
	v_max3_f32 v66, v66, v18, v19
	v_max3_f32 v66, v66, v20, v21
	v_max3_f32 v66, v66, v22, v23
	v_max3_f32 v66, v66, v24, v25
	v_max3_f32 v66, v66, v26, v27
	v_max3_f32 v66, v66, v28, v29
	v_max3_f32 v66, v66, v30, v31
	v_mov_b32_e32 v67, v66
	s_nop 1
	v_permlane32_swap_b32_e32 v66, v67
	v_max_f32_e32 v50, v67, v67
	v_max_f32_e32 v51, v66, v66
	v_max_f32_e32 v50, v51, v50
	v_exp_f32_e32 v32, v32
	v_exp_f32_e64 v150, -v50
	v_exp_f32_e32 v33, v33
	v_exp_f32_e32 v34, v34
	v_exp_f32_e32 v35, v35
	v_exp_f32_e32 v36, v36
	v_exp_f32_e32 v37, v37
	v_exp_f32_e32 v38, v38
	v_exp_f32_e32 v39, v39
	v_exp_f32_e32 v40, v40
	v_exp_f32_e32 v42, v42
	v_exp_f32_e32 v44, v44
	v_exp_f32_e32 v46, v46
	v_exp_f32_e32 v47, v47
	v_exp_f32_e32 v45, v45
	v_exp_f32_e32 v43, v43
	v_exp_f32_e32 v41, v41
	v_sub_f32_e32 v66, v18, v50
	v_sub_f32_e32 v65, v17, v50
	v_sub_f32_e32 v64, v16, v50
	v_lshl_add_u64 v[16:17], s[68:69], 0, v[48:49]
	v_and_b32_e32 v18, 15, v80
	v_lshlrev_b64 v[16:17], 11, v[16:17]
	v_lshlrev_b32_e32 v18, 4, v18
	v_or3_b32 v16, v16, s72, v18
	v_mov_b64_e32 v[12:13], s[24:25]
; #define MFMA32(a, b, c) __builtin_amdgcn_mfma_f32_32x32x16_bf16((a), (b), (c), 0, 0, 0)
; #define SBAR() __builtin_amdgcn_sched_barrier(0)
; #define SLOAD(i, k0) do { sr_[i].vs0 = *(const bf16x8*)(&Vh[(long)((k0) + sr) * LDA_ + sc]); sr_[i].vs1 = *(const bf16x8*)(&Vh[(long)((k0) + 32 + sr) * LDA_ + sc]); \
;     sr_[i].ks0 = *(const bf16x8*)(&Kh[(long)((k0) + sr) * LDA_ + sc]); sr_[i].ks1 = *(const bf16x8*)(&Kh[(long)((k0) + 32 + sr) * LDA_ + sc]); } while (0)
; DI void finishSM(f32x16& p0, f32x16& p1, float alpha, float& l_reg, bf16x8& pa0, bf16x8& pa1, bf16x8& pa2, bf16x8& pa3) {
; #pragma unroll
;     for (int r = 0; r < 16; ++r) p1[r] = __builtin_amdgcn_exp2f(p1[r]);
;     float ps = 0;
; #pragma unroll
;     for (int r = 0; r < 16; ++r) ps += p0[r];
; #pragma unroll
;     for (int r = 0; r < 16; ++r) ps += p1[r];
;     { auto rr = __builtin_amdgcn_permlane32_swap(__float_as_uint(ps), __float_as_uint(ps), false, false);
;       ps = __uint_as_float(rr[0]) + __uint_as_float(rr[1]); }
;     l_reg = l_reg * alpha + ps;
; DI void qkt(f32x16& p0, f32x16& p1, const char* Ks, const bf16x8* qr, float negm, int r32, int hi) {
; #pragma unroll
;     for (int i = 0; i < 16; ++i) { p0[i] = negm; p1[i] = negm; }
; #pragma unroll
;     for (int d0 = 0; d0 < 8; ++d0) { const int cb = (d0 * 16 + hi * 8) * 2;
;         bf16x8 b0 = *(const bf16x8*)(Ks + KSWZ(r32, cb));
;         bf16x8 b1 = *(const bf16x8*)(Ks + KSWZ(32 + r32, cb));
;         p0 = MFMA32(b0, qr[d0], p0);
;         p1 = MFMA32(b1, qr[d0], p1); }
; }
; DI void attn_unit(const bf16_t* __restrict__ Qb, const bf16_t* __restrict__ Kh, const bf16_t* __restrict__ Vh, bf16_t* __restrict__ Ob, const float* __restrict__ onw, int seq, char* lds) {
;     ...
;     for (int j = 1; j + 1 < NT; j += 2) {
;         SBAR(); qkt(pB0, pB1, K_lds + SHM_K, qr, -m_reg, r32, hi);
;         finishSM(pA0, pA1, alA, l_reg, pa0, pa1, pa2, pa3); SBAR();
;         SLOAD(SO, (j + 1) * 64); SBAR();
	v_pk_mul_f32 v[146:147], v[46:47], v[150:151] op_sel_hi:[1,0]
	v_pk_mul_f32 v[160:161], v[44:45], v[150:151] op_sel_hi:[1,0]
	v_pk_mul_f32 v[164:165], v[42:43], v[150:151] op_sel_hi:[1,0]
	v_pk_mul_f32 v[168:169], v[40:41], v[150:151] op_sel_hi:[1,0]
	v_pk_mul_f32 v[156:157], v[38:39], v[150:151] op_sel_hi:[1,0]
	v_pk_mul_f32 v[158:159], v[36:37], v[150:151] op_sel_hi:[1,0]
	v_pk_mul_f32 v[162:163], v[34:35], v[150:151] op_sel_hi:[1,0]
	v_pk_mul_f32 v[166:167], v[32:33], v[150:151] op_sel_hi:[1,0]
	v_sub_f32_e32 v79, v31, v50
	v_sub_f32_e32 v78, v30, v50
	v_sub_f32_e32 v77, v29, v50
	v_sub_f32_e32 v76, v28, v50
	v_sub_f32_e32 v75, v27, v50
	v_sub_f32_e32 v74, v26, v50
	v_sub_f32_e32 v73, v25, v50
	v_sub_f32_e32 v72, v24, v50
	v_sub_f32_e32 v71, v23, v50
	v_sub_f32_e32 v70, v22, v50
	v_sub_f32_e32 v69, v21, v50
	v_sub_f32_e32 v68, v20, v50
	v_sub_f32_e32 v67, v19, v50
	v_add_f32_e32 v215, 0, v50
	v_lshl_add_u64 v[152:153], s[40:41], 0, v[16:17]
	v_mov_b64_e32 v[62:63], v[14:15]
	v_mov_b64_e32 v[30:31], v[14:15]
	v_mov_b64_e32 v[46:47], v[14:15]
	v_mov_b64_e32 v[60:61], v[12:13]
	v_mov_b64_e32 v[58:59], v[10:11]
	v_mov_b64_e32 v[56:57], v[8:9]
	v_mov_b64_e32 v[54:55], v[6:7]
	v_mov_b64_e32 v[52:53], v[4:5]
	v_mov_b64_e32 v[50:51], v[2:3]
	v_mov_b64_e32 v[48:49], v[0:1]
	v_mov_b64_e32 v[28:29], v[12:13]
	v_mov_b64_e32 v[26:27], v[10:11]
	v_mov_b64_e32 v[24:25], v[8:9]
	v_mov_b64_e32 v[22:23], v[6:7]
	v_mov_b64_e32 v[20:21], v[4:5]
	v_mov_b64_e32 v[18:19], v[2:3]
	v_mov_b64_e32 v[16:17], v[0:1]
	v_mov_b64_e32 v[44:45], v[12:13]
	v_mov_b64_e32 v[42:43], v[10:11]
	v_mov_b64_e32 v[40:41], v[8:9]
	v_mov_b64_e32 v[38:39], v[6:7]
	v_mov_b64_e32 v[36:37], v[4:5]
	v_mov_b64_e32 v[34:35], v[2:3]
	v_mov_b64_e32 v[32:33], v[0:1]
.LBB0_580:
	s_add_u32 m0, s100, 0x8000
	s_nop 0
	global_load_lds_dwordx4 v246, s[98:99]
	s_add_u32 m0, s100, 0xa000
	s_nop 0
	global_load_lds_dwordx4 v247, s[98:99]
	s_add_u32 m0, s100, 0x4000
	s_nop 0
	global_load_lds_dwordx4 v248, s[98:99]
	s_add_u32 m0, s100, 0x6000
	s_nop 0
	global_load_lds_dwordx4 v249, s[98:99]
	s_add_u32 s98, s98, 0x20000
	s_addc_u32 s99, s99, 0
	ds_read_b128 v[216:219], v183 offset:49152
	ds_read_b128 v[220:223], v183 offset:57344
	v_xor_b32_e32 v80, 0x80000000, v215
	v_mov_b32_e32 v81, v80
	v_mov_b32_e32 v82, v80
	v_mov_b32_e32 v83, v80
	v_mov_b32_e32 v84, v80
	v_mov_b32_e32 v85, v80
	v_mov_b32_e32 v86, v80
	v_mov_b32_e32 v87, v80
	v_mov_b32_e32 v88, v80
	v_mov_b32_e32 v89, v80
	v_mov_b32_e32 v90, v80
	v_mov_b32_e32 v91, v80
	v_mov_b32_e32 v92, v80
	v_mov_b32_e32 v93, v80
	v_mov_b32_e32 v94, v80
	v_mov_b32_e32 v95, v80
	v_add_f32_e32 v144, 0, v166
	v_add_f32_e32 v144, v167, v144
	s_waitcnt lgkmcnt(1)
	v_mfma_f32_32x32x16_bf16 v[96:111], v[216:219], v[140:143], v[80:95]
	v_add_f32_e32 v144, v162, v144
	v_add_f32_e32 v144, v163, v144
	v_add_f32_e32 v144, v158, v144
	v_add_f32_e32 v144, v159, v144
	v_add_f32_e32 v144, v156, v144
	v_add_f32_e32 v144, v157, v144
	v_add_f32_e32 v144, v168, v144
	s_waitcnt lgkmcnt(0)
	v_mfma_f32_32x32x16_bf16 v[80:95], v[220:223], v[140:143], v[80:95]
	ds_read_b128 v[216:219], v208 offset:49152
	ds_read_b128 v[220:223], v208 offset:57344
	v_add_f32_e32 v144, v169, v144
	v_add_f32_e32 v144, v164, v144
	v_add_f32_e32 v144, v165, v144
	v_exp_f32_e32 v64, v64
	v_add_f32_e32 v144, v160, v144
	v_exp_f32_e32 v65, v65
	s_waitcnt lgkmcnt(0)
	v_mfma_f32_32x32x16_bf16 v[80:95], v[220:223], v[136:139], v[80:95]
	v_add_f32_e32 v144, v161, v144
	v_exp_f32_e32 v66, v66
	v_add_f32_e32 v144, v146, v144
	v_exp_f32_e32 v67, v67
	v_add_f32_e32 v144, v147, v144
	v_exp_f32_e32 v68, v68
	v_add_f32_e32 v144, v64, v144
	v_mfma_f32_32x32x16_bf16 v[96:111], v[216:219], v[136:139], v[96:111]
	ds_read_b128 v[216:219], v209 offset:49152
	ds_read_b128 v[220:223], v209 offset:57344
	v_exp_f32_e32 v69, v69
	v_add_f32_e32 v144, v65, v144
	v_exp_f32_e32 v70, v70
	v_add_f32_e32 v144, v66, v144
	v_exp_f32_e32 v71, v71
	v_add_f32_e32 v144, v67, v144
	s_waitcnt lgkmcnt(0)
	v_mfma_f32_32x32x16_bf16 v[80:95], v[220:223], v[132:135], v[80:95]
	v_exp_f32_e32 v72, v72
	v_add_f32_e32 v144, v68, v144
	v_exp_f32_e32 v73, v73
	v_add_f32_e32 v144, v69, v144
	v_exp_f32_e32 v74, v74
	v_add_f32_e32 v144, v70, v144
	v_exp_f32_e32 v75, v75
	v_mfma_f32_32x32x16_bf16 v[96:111], v[216:219], v[132:135], v[96:111]
	ds_read_b128 v[216:219], v210 offset:49152
	ds_read_b128 v[220:223], v210 offset:57344
	v_add_f32_e32 v144, v71, v144
	v_exp_f32_e32 v76, v76
	v_add_f32_e32 v144, v72, v144
	v_exp_f32_e32 v77, v77
	v_add_f32_e32 v144, v73, v144
	v_exp_f32_e32 v78, v78
	s_waitcnt lgkmcnt(0)
	v_mfma_f32_32x32x16_bf16 v[80:95], v[220:223], v[128:131], v[80:95]
	v_add_f32_e32 v144, v74, v144
	v_exp_f32_e32 v79, v79
	v_add_f32_e32 v144, v75, v144
	v_add_f32_e32 v144, v76, v144
	v_add_f32_e32 v144, v77, v144
	v_add_f32_e32 v144, v78, v144
	v_mfma_f32_32x32x16_bf16 v[96:111], v[216:219], v[128:131], v[96:111]
	ds_read_b128 v[216:219], v211 offset:49152
	ds_read_b128 v[220:223], v211 offset:57344
	s_waitcnt lgkmcnt(0)
	v_mfma_f32_32x32x16_bf16 v[80:95], v[220:223], v[124:127], v[80:95]
	v_mfma_f32_32x32x16_bf16 v[96:111], v[216:219], v[124:127], v[96:111]
	ds_read_b128 v[216:219], v212 offset:49152
	ds_read_b128 v[220:223], v212 offset:57344
	s_waitcnt lgkmcnt(0)
	v_mfma_f32_32x32x16_bf16 v[80:95], v[220:223], v[120:123], v[80:95]
	v_mfma_f32_32x32x16_bf16 v[96:111], v[216:219], v[120:123], v[96:111]
	ds_read_b128 v[216:219], v213 offset:49152
	ds_read_b128 v[220:223], v213 offset:57344
	s_waitcnt lgkmcnt(0)
	v_mfma_f32_32x32x16_bf16 v[80:95], v[220:223], v[116:119], v[80:95]
	v_mfma_f32_32x32x16_bf16 v[96:111], v[216:219], v[116:119], v[96:111]
	ds_read_b128 v[216:219], v214 offset:49152
	ds_read_b128 v[220:223], v214 offset:57344
	s_waitcnt lgkmcnt(0)
; #define MFMA32(a, b, c) __builtin_amdgcn_mfma_f32_32x32x16_bf16((a), (b), (c), 0, 0, 0)
; #define SBAR() __builtin_amdgcn_sched_barrier(0)
; template <int OFF> DI s16x4 tr_read(int vb) { s16x4 r; asm volatile("ds_read_b64_tr_b16 %0, %1 offset:%2" : "=&v"(r) : "v"(vb), "i"(OFF) : "memory"); return r; }
; #define SLOAD(i, k0) do { sr_[i].vs0 = *(const bf16x8*)(&Vh[(long)((k0) + sr) * LDA_ + sc]); sr_[i].vs1 = *(const bf16x8*)(&Vh[(long)((k0) + 32 + sr) * LDA_ + sc]); \
;     sr_[i].ks0 = *(const bf16x8*)(&Kh[(long)((k0) + sr) * LDA_ + sc]); sr_[i].ks1 = *(const bf16x8*)(&Kh[(long)((k0) + 32 + sr) * LDA_ + sc]); } while (0)
; template <int D0> DI void pv_one(f32x16& od, int vb, bf16x8 pa0, bf16x8 pa1, bf16x8 pa2, bf16x8 pa3) {
;     const s16x4 l0 = tr_read<v_rd_off(D0, 0, 0)>(vb), h0 = tr_read<v_rd_off(D0, 0, 1)>(vb), l1 = tr_read<v_rd_off(D0, 1, 0)>(vb), h1 = tr_read<v_rd_off(D0, 1, 1)>(vb);
;     const s16x4 l2 = tr_read<v_rd_off(D0, 2, 0)>(vb), h2 = tr_read<v_rd_off(D0, 2, 1)>(vb), l3 = tr_read<v_rd_off(D0, 3, 0)>(vb), h3 = tr_read<v_rd_off(D0, 3, 1)>(vb);
;     asm volatile("s_waitcnt lgkmcnt(0)" ::: "memory"); SBAR();
;     ...
;     od = MFMA32(pa0, PK(l0, h0), od);
;     od = MFMA32(pa1, PK(l1, h1), od);
;     od = MFMA32(pa2, PK(l2, h2), od);
;     od = MFMA32(pa3, PK(l3, h3), od);
;     ...
; }
; DI float pv_d0_sm(f32x16* o, int vb, bf16x8 pa0, bf16x8 pa1, bf16x8 pa2, bf16x8 pa3, f32x16& q0, f32x16& q1) {
;     pv_one<0>(o[0], vb, pa0, pa1, pa2, pa3); const float mx0 = smA_max0(q0);
;     pv_one<1>(o[1], vb, pa0, pa1, pa2, pa3); const float pmax = smA_max1(mx0, q1);
;     pv_one<2>(o[2], vb, pa0, pa1, pa2, pa3); smA_exp<0>(q0);
;     pv_one<3>(o[3], vb, pa0, pa1, pa2, pa3); smA_exp<8>(q0);
;     return pmax;
; }
; DI void attn_unit(const bf16_t* __restrict__ Qb, const bf16_t* __restrict__ Kh, const bf16_t* __restrict__ Vh, bf16_t* __restrict__ Ob, const float* __restrict__ onw, int seq, char* lds) {
;     ...
;         finishSM(pA0, pA1, alA, l_reg, pa0, pa1, pa2, pa3); SBAR();
;         SLOAD(SO, (j + 1) * 64); SBAR();
;         { const float pm = pv_d0_sm(o, vb0, pa0, pa1, pa2, pa3, pB0, pB1); smB<false>(pB0, pB1, pm, m_reg, alB); }
	v_mfma_f32_32x32x16_bf16 v[80:95], v[220:223], v[112:115], v[80:95]
	v_mfma_f32_32x32x16_bf16 v[96:111], v[216:219], v[112:115], v[96:111]
	v_add_f32_e32 v216, v79, v144
	v_mov_b32_e32 v217, v216
	v_cvt_pk_bf16_f32 v218, v166, v167
	v_cvt_pk_bf16_f32 v219, v162, v163
	v_cvt_pk_bf16_f32 v220, v158, v159
	v_cvt_pk_bf16_f32 v221, v156, v157
	v_cvt_pk_bf16_f32 v162, v168, v169
	v_cvt_pk_bf16_f32 v163, v164, v165
	v_cvt_pk_bf16_f32 v164, v160, v161
	v_cvt_pk_bf16_f32 v165, v146, v147
	s_nop 1
	v_permlane32_swap_b32_e32 v216, v217
	v_permlane32_swap_b32_e32 v162, v164
	v_permlane32_swap_b32_e32 v163, v165
	v_cvt_pk_bf16_f32 v222, v64, v65
	v_cvt_pk_bf16_f32 v223, v66, v67
	v_cvt_pk_bf16_f32 v224, v68, v69
	v_cvt_pk_bf16_f32 v225, v70, v71
	v_cvt_pk_bf16_f32 v226, v72, v73
	v_cvt_pk_bf16_f32 v227, v74, v75
	v_cvt_pk_bf16_f32 v228, v76, v77
	v_cvt_pk_bf16_f32 v229, v78, v79
	v_permlane32_swap_b32_e32 v218, v220
	v_permlane32_swap_b32_e32 v219, v221
	v_permlane32_swap_b32_e32 v222, v224
	v_permlane32_swap_b32_e32 v223, v225
	v_permlane32_swap_b32_e32 v226, v228
	v_permlane32_swap_b32_e32 v227, v229
	ds_read_b64_tr_b16 v[144:145], v175 offset:0
	ds_read_b64_tr_b16 v[146:147], v175 offset:0x800
	ds_read_b64_tr_b16 v[156:157], v175 offset:0x1000
	ds_read_b64_tr_b16 v[158:159], v175 offset:0x1800
	ds_read_b64_tr_b16 v[166:167], v175 offset:0x2000
	ds_read_b64_tr_b16 v[168:169], v175 offset:0x2800
	ds_read_b64_tr_b16 v[230:231], v175 offset:0x3000
	ds_read_b64_tr_b16 v[232:233], v175 offset:0x3800
	s_waitcnt lgkmcnt(0)
	s_nop 0
	v_mfma_f32_32x32x16_bf16 v[0:15], v[218:221], v[144:147], v[0:15]
	v_max_f32_e32 v144, v97, v97
	v_max_f32_e32 v145, v96, v96
	v_max_f32_e32 v144, v145, v144
	v_max3_f32 v144, v144, v98, v99
	v_max3_f32 v144, v144, v100, v101
	v_max3_f32 v144, v144, v102, v103
	v_max3_f32 v144, v144, v104, v105
	v_mfma_f32_32x32x16_bf16 v[0:15], v[162:165], v[156:159], v[0:15]
	v_max3_f32 v144, v144, v106, v107
	v_max3_f32 v146, v144, v108, v109
	ds_read_b64_tr_b16 v[144:145], v175 offset:0x200
	v_max3_f32 v154, v146, v110, v111
	ds_read_b64_tr_b16 v[146:147], v175 offset:0xa00
	ds_read_b64_tr_b16 v[156:157], v175 offset:0x1200
	ds_read_b64_tr_b16 v[158:159], v175 offset:0x1a00
	v_mfma_f32_32x32x16_bf16 v[0:15], v[222:225], v[166:169], v[0:15]
	ds_read_b64_tr_b16 v[234:235], v175 offset:0x2200
	ds_read_b64_tr_b16 v[236:237], v175 offset:0x2a00
	ds_read_b64_tr_b16 v[238:239], v175 offset:0x3200
	ds_read_b64_tr_b16 v[240:241], v175 offset:0x3a00
	s_waitcnt lgkmcnt(0)
	v_mfma_f32_32x32x16_bf16 v[0:15], v[226:229], v[230:233], v[0:15]
	v_mfma_f32_32x32x16_bf16 v[48:63], v[218:221], v[144:147], v[48:63]
	v_max3_f32 v154, v154, v80, v81
	v_max3_f32 v144, v154, v82, v83
	v_max3_f32 v144, v144, v84, v85
	v_max3_f32 v144, v144, v86, v87
	v_max3_f32 v144, v144, v88, v89
	v_max3_f32 v144, v144, v90, v91
	v_max3_f32 v144, v144, v92, v93
	v_mfma_f32_32x32x16_bf16 v[48:63], v[162:165], v[156:159], v[48:63]
	v_max3_f32 v144, v144, v94, v95
	v_mov_b32_e32 v145, v144
	s_nop 1
	v_permlane32_swap_b32_e32 v144, v145
	v_max_f32_e32 v145, v145, v145
	v_max_f32_e32 v144, v144, v144
	v_max_f32_e32 v168, v144, v145
	v_mfma_f32_32x32x16_bf16 v[48:63], v[222:225], v[234:237], v[48:63]
	ds_read_b64_tr_b16 v[144:145], v175 offset:0x400
	ds_read_b64_tr_b16 v[146:147], v175 offset:0xc00
	ds_read_b64_tr_b16 v[156:157], v175 offset:0x1400
	ds_read_b64_tr_b16 v[158:159], v175 offset:0x1c00
	ds_read_b64_tr_b16 v[230:231], v175 offset:0x2400
	ds_read_b64_tr_b16 v[232:233], v175 offset:0x2c00
	ds_read_b64_tr_b16 v[234:235], v175 offset:0x3400
	v_mfma_f32_32x32x16_bf16 v[48:63], v[226:229], v[238:241], v[48:63]
	ds_read_b64_tr_b16 v[236:237], v175 offset:0x3c00
	s_waitcnt lgkmcnt(0)
	v_mfma_f32_32x32x16_bf16 v[16:31], v[218:221], v[144:147], v[16:31]
	v_exp_f32_e32 v144, v96
	v_exp_f32_e32 v145, v97
	ds_read_b64_tr_b16 v[96:97], v175 offset:0x600
	v_exp_f32_e32 v146, v100
	v_exp_f32_e32 v147, v101
	v_mfma_f32_32x32x16_bf16 v[16:31], v[162:165], v[156:159], v[16:31]
	v_exp_f32_e32 v158, v98
	v_exp_f32_e32 v159, v99
	ds_read_b64_tr_b16 v[98:99], v175 offset:0xe00
	ds_read_b64_tr_b16 v[100:101], v175 offset:0x1600
	v_exp_f32_e32 v156, v102
	v_exp_f32_e32 v157, v103
	ds_read_b64_tr_b16 v[102:103], v175 offset:0x1e00
	v_mfma_f32_32x32x16_bf16 v[16:31], v[222:225], v[230:233], v[16:31]
	ds_read_b64_tr_b16 v[230:231], v175 offset:0x2600
	ds_read_b64_tr_b16 v[232:233], v175 offset:0x2e00
	ds_read_b64_tr_b16 v[238:239], v175 offset:0x3600
	ds_read_b64_tr_b16 v[240:241], v175 offset:0x3e00
	s_waitcnt lgkmcnt(0)
	v_mfma_f32_32x32x16_bf16 v[16:31], v[226:229], v[234:237], v[16:31]
	v_mfma_f32_32x32x16_bf16 v[32:47], v[218:221], v[96:99], v[32:47]
	v_exp_f32_e32 v166, v104
	v_exp_f32_e32 v167, v105
	v_exp_f32_e32 v160, v110
	v_exp_f32_e32 v161, v111
	v_cmp_ge_f32_e32 vcc, s82, v168
	v_mov_b32_e32 v154, 1.0
	s_cmp_eq_u64 vcc, exec
	v_mfma_f32_32x32x16_bf16 v[32:47], v[162:165], v[100:103], v[32:47]
	v_exp_f32_e32 v162, v106
	v_exp_f32_e32 v163, v107
	v_exp_f32_e32 v164, v108
	v_exp_f32_e32 v165, v109
	v_mfma_f32_32x32x16_bf16 v[32:47], v[222:225], v[230:233], v[32:47]
	v_mfma_f32_32x32x16_bf16 v[32:47], v[226:229], v[238:241], v[32:47]
	s_cbranch_scc0 .LBB0_593
; #define SBAR() __builtin_amdgcn_sched_barrier(0)
; #define SWRITE(b, i) do { *(bf16x8*)(V_lds + (b) * SHM_V + vst0) = sr_[i].vs0;          \
;     *(bf16x8*)(V_lds + (b) * SHM_V + vst1) = sr_[i].vs1; int kc = sc * 2;               \
;     *(bf16x8*)(K_lds + (b) * SHM_K + KSWZ(sr, kc)) = sr_[i].ks0;                       \
;     *(bf16x8*)(K_lds + (b) * SHM_K + KSWZ(32 + sr, kc)) = sr_[i].ks1; } while (0)
; #define SWAIT() asm volatile("s_waitcnt vmcnt(0)" ::: "memory")
; #define RESC(a) do { if (__any((a) < 1.f)) { if (hi == 0) al_l[r32] = (a); asm volatile("s_waitcnt lgkmcnt(0)" ::: "memory"); \
;     _Pragma("unroll") for (int d = 0; d < 4; ++d) _Pragma("unroll") for (int r = 0; r < 16; ++r) o[d][r] *= al_l[crow(r, hi)]; } } while (0)
; DI void attn_unit(const bf16_t* __restrict__ Qb, const bf16_t* __restrict__ Kh, const bf16_t* __restrict__ Vh, bf16_t* __restrict__ Ob, const float* __restrict__ onw, int seq, char* lds) {
;     ...
;         __syncthreads(); SWAIT(); SWRITE(0, SE);
;         RESC(alB); __syncthreads();
;         SBAR(); qkt(pA0, pA1, K_lds, qr, -m_reg, r32, hi);
.LBB0_581:
	s_waitcnt vmcnt(0)
	v_cmp_gt_f32_e32 vcc, 1.0, v154
	s_waitcnt lgkmcnt(0)
	s_barrier
	s_add_u32 m0, s100, 0xc000
	s_nop 0
	global_load_lds_dwordx4 v246, s[98:99]
	s_add_u32 m0, s100, 0xe000
	s_nop 0
	global_load_lds_dwordx4 v247, s[98:99]
	s_mov_b32 m0, s100
	s_nop 0
	global_load_lds_dwordx4 v248, s[98:99]
	s_add_u32 m0, s100, 0x2000
	s_nop 0
	global_load_lds_dwordx4 v249, s[98:99]
	s_add_u32 s98, s98, 0x20000
	s_addc_u32 s99, s99, 0
	s_cbranch_vccz .LBB0_585
	s_and_saveexec_b64 s[14:15], s[2:3]
	ds_write_b32 v172, v154 offset:128
	s_or_b64 exec, exec, s[14:15]
	s_waitcnt lgkmcnt(0)
	v_add_u32_e32 v76, v171, v184
	ds_read_b128 v[64:67], v76 offset:224
	ds_read_b128 v[68:71], v76 offset:192
	ds_read_b128 v[72:75], v76 offset:160
	ds_read_b128 v[76:79], v76 offset:128
	s_waitcnt lgkmcnt(3)
	v_pk_mul_f32 v[12:13], v[12:13], v[64:65]
	s_waitcnt lgkmcnt(2)
	v_pk_mul_f32 v[8:9], v[8:9], v[68:69]
	s_waitcnt lgkmcnt(1)
	v_pk_mul_f32 v[4:5], v[4:5], v[72:73]
	v_pk_mul_f32 v[14:15], v[14:15], v[66:67]
	v_pk_mul_f32 v[10:11], v[10:11], v[70:71]
	v_pk_mul_f32 v[6:7], v[6:7], v[74:75]
	s_waitcnt lgkmcnt(0)
	v_pk_mul_f32 v[2:3], v[2:3], v[78:79]
	v_pk_mul_f32 v[0:1], v[0:1], v[76:77]
	v_pk_mul_f32 v[60:61], v[60:61], v[64:65]
	v_pk_mul_f32 v[56:57], v[56:57], v[68:69]
	v_pk_mul_f32 v[52:53], v[52:53], v[72:73]
	v_pk_mul_f32 v[62:63], v[62:63], v[66:67]
	v_pk_mul_f32 v[58:59], v[58:59], v[70:71]
	v_pk_mul_f32 v[54:55], v[54:55], v[74:75]
	v_pk_mul_f32 v[50:51], v[50:51], v[78:79]
	v_pk_mul_f32 v[48:49], v[48:49], v[76:77]
	v_pk_mul_f32 v[28:29], v[28:29], v[64:65]
	v_pk_mul_f32 v[24:25], v[24:25], v[68:69]
	v_pk_mul_f32 v[20:21], v[20:21], v[72:73]
	v_pk_mul_f32 v[30:31], v[30:31], v[66:67]
	v_pk_mul_f32 v[26:27], v[26:27], v[70:71]
	v_pk_mul_f32 v[22:23], v[22:23], v[74:75]
	v_pk_mul_f32 v[18:19], v[18:19], v[78:79]
	v_pk_mul_f32 v[16:17], v[16:17], v[76:77]
	v_pk_mul_f32 v[44:45], v[44:45], v[64:65]
	v_pk_mul_f32 v[40:41], v[40:41], v[68:69]
	v_pk_mul_f32 v[36:37], v[36:37], v[72:73]
	v_pk_mul_f32 v[46:47], v[46:47], v[66:67]
	v_pk_mul_f32 v[42:43], v[42:43], v[70:71]
	v_pk_mul_f32 v[38:39], v[38:39], v[74:75]
	v_pk_mul_f32 v[34:35], v[34:35], v[78:79]
	v_pk_mul_f32 v[32:33], v[32:33], v[76:77]
.LBB0_585:
	ds_read_b128 v[218:221], v183 offset:32768
	ds_read_b128 v[222:225], v183 offset:40960
	v_xor_b32_e32 v64, 0x80000000, v215
	v_mov_b32_e32 v65, v64
	v_mov_b32_e32 v66, v64
	v_mov_b32_e32 v67, v64
	v_mov_b32_e32 v68, v64
	v_mov_b32_e32 v69, v64
	v_mov_b32_e32 v70, v64
	v_mov_b32_e32 v71, v64
	v_mov_b32_e32 v72, v64
	v_mov_b32_e32 v73, v64
	v_mov_b32_e32 v74, v64
	v_mov_b32_e32 v75, v64
	v_mov_b32_e32 v76, v64
	v_mov_b32_e32 v77, v64
	v_mov_b32_e32 v78, v64
	v_mov_b32_e32 v79, v64
	v_add_f32_e32 v168, 0, v144
	v_add_f32_e32 v168, v145, v168
	s_waitcnt lgkmcnt(1)
	v_mfma_f32_32x32x16_bf16 v[96:111], v[218:221], v[140:143], v[64:79]
	v_add_f32_e32 v168, v158, v168
	v_add_f32_e32 v168, v159, v168
	v_add_f32_e32 v168, v146, v168
	v_add_f32_e32 v168, v147, v168
	v_add_f32_e32 v168, v156, v168
	v_add_f32_e32 v168, v157, v168
	v_add_f32_e32 v168, v166, v168
	s_waitcnt lgkmcnt(0)
	v_mfma_f32_32x32x16_bf16 v[64:79], v[222:225], v[140:143], v[64:79]
	ds_read_b128 v[218:221], v208 offset:32768
	ds_read_b128 v[222:225], v208 offset:40960
	v_add_f32_e32 v168, v167, v168
	v_add_f32_e32 v168, v162, v168
	v_add_f32_e32 v168, v163, v168
	v_exp_f32_e32 v80, v80
	v_add_f32_e32 v168, v164, v168
	v_exp_f32_e32 v81, v81
	s_waitcnt lgkmcnt(0)
	v_mfma_f32_32x32x16_bf16 v[64:79], v[222:225], v[136:139], v[64:79]
	v_add_f32_e32 v168, v165, v168
	v_exp_f32_e32 v82, v82
	v_add_f32_e32 v168, v160, v168
	v_exp_f32_e32 v83, v83
	v_add_f32_e32 v168, v161, v168
	v_exp_f32_e32 v84, v84
	v_add_f32_e32 v168, v80, v168
	v_mfma_f32_32x32x16_bf16 v[96:111], v[218:221], v[136:139], v[96:111]
	ds_read_b128 v[218:221], v209 offset:32768
	ds_read_b128 v[222:225], v209 offset:40960
	v_exp_f32_e32 v85, v85
	v_add_f32_e32 v168, v81, v168
	v_exp_f32_e32 v86, v86
	v_add_f32_e32 v168, v82, v168
	v_exp_f32_e32 v87, v87
	v_add_f32_e32 v168, v83, v168
	s_waitcnt lgkmcnt(0)
	v_mfma_f32_32x32x16_bf16 v[64:79], v[222:225], v[132:135], v[64:79]
	v_exp_f32_e32 v88, v88
	v_add_f32_e32 v168, v84, v168
	v_exp_f32_e32 v89, v89
	v_add_f32_e32 v168, v85, v168
	v_exp_f32_e32 v90, v90
	v_add_f32_e32 v168, v86, v168
	v_exp_f32_e32 v91, v91
	v_mfma_f32_32x32x16_bf16 v[96:111], v[218:221], v[132:135], v[96:111]
	ds_read_b128 v[218:221], v210 offset:32768
	ds_read_b128 v[222:225], v210 offset:40960
	v_add_f32_e32 v168, v87, v168
	v_exp_f32_e32 v92, v92
	v_add_f32_e32 v168, v88, v168
	v_exp_f32_e32 v93, v93
	v_add_f32_e32 v168, v89, v168
	v_exp_f32_e32 v94, v94
	s_waitcnt lgkmcnt(0)
	v_mfma_f32_32x32x16_bf16 v[64:79], v[222:225], v[128:131], v[64:79]
	v_add_f32_e32 v168, v90, v168
	v_exp_f32_e32 v95, v95
	v_add_f32_e32 v168, v91, v168
	v_add_f32_e32 v168, v92, v168
	v_add_f32_e32 v168, v93, v168
	v_add_f32_e32 v168, v94, v168
	v_mfma_f32_32x32x16_bf16 v[96:111], v[218:221], v[128:131], v[96:111]
	ds_read_b128 v[218:221], v211 offset:32768
	ds_read_b128 v[222:225], v211 offset:40960
	s_waitcnt lgkmcnt(0)
	v_mfma_f32_32x32x16_bf16 v[64:79], v[222:225], v[124:127], v[64:79]
	v_mfma_f32_32x32x16_bf16 v[96:111], v[218:221], v[124:127], v[96:111]
	ds_read_b128 v[218:221], v212 offset:32768
	ds_read_b128 v[222:225], v212 offset:40960
	s_waitcnt lgkmcnt(0)
	v_mfma_f32_32x32x16_bf16 v[64:79], v[222:225], v[120:123], v[64:79]
	v_mfma_f32_32x32x16_bf16 v[96:111], v[218:221], v[120:123], v[96:111]
	ds_read_b128 v[218:221], v213 offset:32768
	ds_read_b128 v[222:225], v213 offset:40960
	s_waitcnt lgkmcnt(0)
; #define MFMA32(a, b, c) __builtin_amdgcn_mfma_f32_32x32x16_bf16((a), (b), (c), 0, 0, 0)
; #define SBAR() __builtin_amdgcn_sched_barrier(0)
; template <int OFF> DI s16x4 tr_read(int vb) { s16x4 r; asm volatile("ds_read_b64_tr_b16 %0, %1 offset:%2" : "=&v"(r) : "v"(vb), "i"(OFF) : "memory"); return r; }
; #define SLOAD(i, k0) do { sr_[i].vs0 = *(const bf16x8*)(&Vh[(long)((k0) + sr) * LDA_ + sc]); sr_[i].vs1 = *(const bf16x8*)(&Vh[(long)((k0) + 32 + sr) * LDA_ + sc]); \
;     sr_[i].ks0 = *(const bf16x8*)(&Kh[(long)((k0) + sr) * LDA_ + sc]); sr_[i].ks1 = *(const bf16x8*)(&Kh[(long)((k0) + 32 + sr) * LDA_ + sc]); } while (0)
; template <int D0> DI void pv_one(f32x16& od, int vb, bf16x8 pa0, bf16x8 pa1, bf16x8 pa2, bf16x8 pa3) {
;     const s16x4 l0 = tr_read<v_rd_off(D0, 0, 0)>(vb), h0 = tr_read<v_rd_off(D0, 0, 1)>(vb), l1 = tr_read<v_rd_off(D0, 1, 0)>(vb), h1 = tr_read<v_rd_off(D0, 1, 1)>(vb);
;     const s16x4 l2 = tr_read<v_rd_off(D0, 2, 0)>(vb), h2 = tr_read<v_rd_off(D0, 2, 1)>(vb), l3 = tr_read<v_rd_off(D0, 3, 0)>(vb), h3 = tr_read<v_rd_off(D0, 3, 1)>(vb);
;     asm volatile("s_waitcnt lgkmcnt(0)" ::: "memory"); SBAR();
;     ...
;     od = MFMA32(pa0, PK(l0, h0), od);
;     od = MFMA32(pa1, PK(l1, h1), od);
;     od = MFMA32(pa2, PK(l2, h2), od);
;     od = MFMA32(pa3, PK(l3, h3), od);
;     ...
; }
; DI float pv_d0_sm(f32x16* o, int vb, bf16x8 pa0, bf16x8 pa1, bf16x8 pa2, bf16x8 pa3, f32x16& q0, f32x16& q1) {
;     pv_one<0>(o[0], vb, pa0, pa1, pa2, pa3); const float mx0 = smA_max0(q0);
;     pv_one<1>(o[1], vb, pa0, pa1, pa2, pa3); const float pmax = smA_max1(mx0, q1);
;     pv_one<2>(o[2], vb, pa0, pa1, pa2, pa3); smA_exp<0>(q0);
;     pv_one<3>(o[3], vb, pa0, pa1, pa2, pa3); smA_exp<8>(q0);
;     return pmax;
; }
; DI void attn_unit(const bf16_t* __restrict__ Qb, const bf16_t* __restrict__ Kh, const bf16_t* __restrict__ Vh, bf16_t* __restrict__ Ob, const float* __restrict__ onw, int seq, char* lds) {
;     ...
;         finishSM(pB0, pB1, alB, l_reg, pa0, pa1, pa2, pa3); SBAR();
;         SLOAD(SE, (j + 2) * 64); SBAR();
;         { const float pm = pv_d0_sm(o, vb0 + (int)SHM_V, pa0, pa1, pa2, pa3, pA0, pA1); smB<false>(pA0, pA1, pm, m_reg, alA); }
	v_mfma_f32_32x32x16_bf16 v[64:79], v[222:225], v[116:119], v[64:79]
	v_mfma_f32_32x32x16_bf16 v[96:111], v[218:221], v[116:119], v[96:111]
	ds_read_b128 v[218:221], v214 offset:32768
	ds_read_b128 v[222:225], v214 offset:40960
	v_cvt_pk_bf16_f32 v144, v144, v145
	v_cvt_pk_bf16_f32 v145, v158, v159
	v_cvt_pk_bf16_f32 v146, v146, v147
	v_cvt_pk_bf16_f32 v147, v156, v157
	s_nop 0
	v_permlane32_swap_b32_e32 v144, v146
	s_waitcnt lgkmcnt(0)
	v_mfma_f32_32x32x16_bf16 v[64:79], v[222:225], v[112:115], v[64:79]
	v_permlane32_swap_b32_e32 v145, v147
	v_cvt_pk_bf16_f32 v222, v166, v167
	v_cvt_pk_bf16_f32 v223, v162, v163
	v_cvt_pk_bf16_f32 v224, v164, v165
	v_cvt_pk_bf16_f32 v225, v160, v161
	v_cvt_pk_bf16_f32 v226, v80, v81
	v_mfma_f32_32x32x16_bf16 v[96:111], v[218:221], v[112:115], v[96:111]
	v_add_f32_e32 v218, v95, v168
	v_mov_b32_e32 v219, v218
	s_nop 1
	v_permlane32_swap_b32_e32 v218, v219
	v_cvt_pk_bf16_f32 v227, v82, v83
	v_cvt_pk_bf16_f32 v228, v84, v85
	v_cvt_pk_bf16_f32 v229, v86, v87
	v_cvt_pk_bf16_f32 v230, v88, v89
	v_cvt_pk_bf16_f32 v231, v90, v91
	v_cvt_pk_bf16_f32 v232, v92, v93
	v_cvt_pk_bf16_f32 v233, v94, v95
	v_permlane32_swap_b32_e32 v222, v224
	v_permlane32_swap_b32_e32 v223, v225
	v_permlane32_swap_b32_e32 v226, v228
	v_permlane32_swap_b32_e32 v227, v229
	v_permlane32_swap_b32_e32 v230, v232
	v_permlane32_swap_b32_e32 v231, v233
	ds_read_b64_tr_b16 v[156:157], v174 offset:0
	ds_read_b64_tr_b16 v[158:159], v174 offset:0x800
	ds_read_b64_tr_b16 v[160:161], v174 offset:0x1000
	ds_read_b64_tr_b16 v[162:163], v174 offset:0x1800
	ds_read_b64_tr_b16 v[164:165], v174 offset:0x2000
	ds_read_b64_tr_b16 v[166:167], v174 offset:0x2800
	ds_read_b64_tr_b16 v[234:235], v174 offset:0x3000
	ds_read_b64_tr_b16 v[236:237], v174 offset:0x3800
	s_waitcnt lgkmcnt(0)
	s_nop 0
	v_mfma_f32_32x32x16_bf16 v[0:15], v[144:147], v[156:159], v[0:15]
	v_max_f32_e32 v156, v97, v97
	v_max_f32_e32 v157, v96, v96
	v_max_f32_e32 v156, v157, v156
	v_max3_f32 v156, v156, v98, v99
	v_max3_f32 v156, v156, v100, v101
	v_max3_f32 v156, v156, v102, v103
	v_max3_f32 v156, v156, v104, v105
	v_mfma_f32_32x32x16_bf16 v[0:15], v[222:225], v[160:163], v[0:15]
	v_max3_f32 v156, v156, v106, v107
	v_max3_f32 v158, v156, v108, v109
	ds_read_b64_tr_b16 v[156:157], v174 offset:0x200
	v_max3_f32 v168, v158, v110, v111
	ds_read_b64_tr_b16 v[158:159], v174 offset:0xa00
	ds_read_b64_tr_b16 v[160:161], v174 offset:0x1200
	ds_read_b64_tr_b16 v[162:163], v174 offset:0x1a00
	v_mfma_f32_32x32x16_bf16 v[0:15], v[226:229], v[164:167], v[0:15]
	ds_read_b64_tr_b16 v[164:165], v174 offset:0x2200
	ds_read_b64_tr_b16 v[166:167], v174 offset:0x2a00
	ds_read_b64_tr_b16 v[238:239], v174 offset:0x3200
	ds_read_b64_tr_b16 v[240:241], v174 offset:0x3a00
	s_waitcnt lgkmcnt(0)
	v_mfma_f32_32x32x16_bf16 v[0:15], v[230:233], v[234:237], v[0:15]
	v_mfma_f32_32x32x16_bf16 v[48:63], v[144:147], v[156:159], v[48:63]
	v_max3_f32 v168, v168, v64, v65
	v_max3_f32 v156, v168, v66, v67
	v_max3_f32 v156, v156, v68, v69
	v_max3_f32 v156, v156, v70, v71
	v_max3_f32 v156, v156, v72, v73
	v_max3_f32 v156, v156, v74, v75
	v_max3_f32 v156, v156, v76, v77
	v_mfma_f32_32x32x16_bf16 v[48:63], v[222:225], v[160:163], v[48:63]
	v_max3_f32 v156, v156, v78, v79
	v_mov_b32_e32 v157, v156
	s_nop 1
	v_permlane32_swap_b32_e32 v156, v157
	v_max_f32_e32 v157, v157, v157
	v_max_f32_e32 v156, v156, v156
	v_max_f32_e32 v220, v156, v157
	v_mfma_f32_32x32x16_bf16 v[48:63], v[226:229], v[164:167], v[48:63]
	ds_read_b64_tr_b16 v[156:157], v174 offset:0x400
	ds_read_b64_tr_b16 v[158:159], v174 offset:0xc00
	ds_read_b64_tr_b16 v[160:161], v174 offset:0x1400
	ds_read_b64_tr_b16 v[162:163], v174 offset:0x1c00
	ds_read_b64_tr_b16 v[234:235], v174 offset:0x2400
	ds_read_b64_tr_b16 v[236:237], v174 offset:0x2c00
	ds_read_b64_tr_b16 v[242:243], v174 offset:0x3400
	v_mfma_f32_32x32x16_bf16 v[48:63], v[230:233], v[238:241], v[48:63]
	ds_read_b64_tr_b16 v[244:245], v174 offset:0x3c00
	s_waitcnt lgkmcnt(0)
	v_mfma_f32_32x32x16_bf16 v[16:31], v[144:147], v[156:159], v[16:31]
	v_exp_f32_e32 v166, v96
	v_exp_f32_e32 v167, v97
	ds_read_b64_tr_b16 v[96:97], v174 offset:0x600
	v_exp_f32_e32 v158, v100
	v_exp_f32_e32 v159, v101
	v_exp_f32_e32 v156, v102
	v_exp_f32_e32 v157, v103
	v_mfma_f32_32x32x16_bf16 v[16:31], v[222:225], v[160:163], v[16:31]
	v_exp_f32_e32 v162, v98
	v_exp_f32_e32 v163, v99
	ds_read_b64_tr_b16 v[98:99], v174 offset:0xe00
	ds_read_b64_tr_b16 v[100:101], v174 offset:0x1600
	ds_read_b64_tr_b16 v[102:103], v174 offset:0x1e00
	v_mfma_f32_32x32x16_bf16 v[16:31], v[226:229], v[234:237], v[16:31]
	ds_read_b64_tr_b16 v[234:235], v174 offset:0x2600
	ds_read_b64_tr_b16 v[236:237], v174 offset:0x2e00
	ds_read_b64_tr_b16 v[238:239], v174 offset:0x3600
	ds_read_b64_tr_b16 v[240:241], v174 offset:0x3e00
	s_waitcnt lgkmcnt(0)
	v_mfma_f32_32x32x16_bf16 v[16:31], v[230:233], v[242:245], v[16:31]
	v_mfma_f32_32x32x16_bf16 v[32:47], v[144:147], v[96:99], v[32:47]
	v_exp_f32_e32 v168, v104
	v_exp_f32_e32 v169, v105
	v_exp_f32_e32 v164, v106
	v_exp_f32_e32 v165, v107
	v_exp_f32_e32 v160, v108
	v_exp_f32_e32 v161, v109
	v_exp_f32_e32 v146, v110
	v_mfma_f32_32x32x16_bf16 v[32:47], v[222:225], v[100:103], v[32:47]
	v_exp_f32_e32 v147, v111
	v_cmp_ge_f32_e32 vcc, s82, v220
	s_cmp_eq_u64 vcc, exec
	v_mfma_f32_32x32x16_bf16 v[32:47], v[226:229], v[234:237], v[32:47]
	v_mfma_f32_32x32x16_bf16 v[32:47], v[230:233], v[238:241], v[32:47]
	s_cbranch_scc0 .LBB0_594
	v_mov_b32_e32 v144, 1.0
; #define SWRITE(b, i) do { *(bf16x8*)(V_lds + (b) * SHM_V + vst0) = sr_[i].vs0;          \
;     *(bf16x8*)(V_lds + (b) * SHM_V + vst1) = sr_[i].vs1; int kc = sc * 2;               \
;     *(bf16x8*)(K_lds + (b) * SHM_K + KSWZ(sr, kc)) = sr_[i].ks0;                       \
;     *(bf16x8*)(K_lds + (b) * SHM_K + KSWZ(32 + sr, kc)) = sr_[i].ks1; } while (0)
; #define SWAIT() asm volatile("s_waitcnt vmcnt(0)" ::: "memory")
; #define RESC(a) do { if (__any((a) < 1.f)) { if (hi == 0) al_l[r32] = (a); asm volatile("s_waitcnt lgkmcnt(0)" ::: "memory"); \
;     _Pragma("unroll") for (int d = 0; d < 4; ++d) _Pragma("unroll") for (int r = 0; r < 16; ++r) o[d][r] *= al_l[crow(r, hi)]; } } while (0)
; DI void attn_unit(const bf16_t* __restrict__ Qb, const bf16_t* __restrict__ Kh, const bf16_t* __restrict__ Vh, bf16_t* __restrict__ Ob, const float* __restrict__ onw, int seq, char* lds) {
;     ...
;         __syncthreads(); SWAIT(); SWRITE(1, SO);
;         RESC(alA); __syncthreads();
.LBB0_587:
	s_waitcnt vmcnt(0)
	v_cmp_gt_f32_e32 vcc, 1.0, v144
	s_waitcnt lgkmcnt(0)
	s_barrier
	s_cbranch_vccz .LBB0_591
	s_and_saveexec_b64 s[14:15], s[2:3]
	ds_write_b32 v172, v144 offset:128
	s_or_b64 exec, exec, s[14:15]
	s_waitcnt lgkmcnt(0)
	v_add_u32_e32 v92, v171, v184
	ds_read_b128 v[80:83], v92 offset:224
	ds_read_b128 v[84:87], v92 offset:192
	ds_read_b128 v[88:91], v92 offset:160
	ds_read_b128 v[92:95], v92 offset:128
	s_waitcnt lgkmcnt(3)
	v_pk_mul_f32 v[12:13], v[12:13], v[80:81]
	s_waitcnt lgkmcnt(2)
	v_pk_mul_f32 v[8:9], v[8:9], v[84:85]
	s_waitcnt lgkmcnt(1)
	v_pk_mul_f32 v[4:5], v[4:5], v[88:89]
	v_pk_mul_f32 v[14:15], v[14:15], v[82:83]
	v_pk_mul_f32 v[10:11], v[10:11], v[86:87]
	v_pk_mul_f32 v[6:7], v[6:7], v[90:91]
	s_waitcnt lgkmcnt(0)
	v_pk_mul_f32 v[2:3], v[2:3], v[94:95]
	v_pk_mul_f32 v[0:1], v[0:1], v[92:93]
	v_pk_mul_f32 v[60:61], v[60:61], v[80:81]
	v_pk_mul_f32 v[56:57], v[56:57], v[84:85]
	v_pk_mul_f32 v[52:53], v[52:53], v[88:89]
	v_pk_mul_f32 v[62:63], v[62:63], v[82:83]
	v_pk_mul_f32 v[58:59], v[58:59], v[86:87]
	v_pk_mul_f32 v[54:55], v[54:55], v[90:91]
	v_pk_mul_f32 v[50:51], v[50:51], v[94:95]
	v_pk_mul_f32 v[48:49], v[48:49], v[92:93]
	v_pk_mul_f32 v[28:29], v[28:29], v[80:81]
	v_pk_mul_f32 v[24:25], v[24:25], v[84:85]
	v_pk_mul_f32 v[20:21], v[20:21], v[88:89]
	v_pk_mul_f32 v[30:31], v[30:31], v[82:83]
	v_pk_mul_f32 v[26:27], v[26:27], v[86:87]
	v_pk_mul_f32 v[22:23], v[22:23], v[90:91]
	v_pk_mul_f32 v[18:19], v[18:19], v[94:95]
	v_pk_mul_f32 v[16:17], v[16:17], v[92:93]
	v_pk_mul_f32 v[44:45], v[44:45], v[80:81]
	v_pk_mul_f32 v[40:41], v[40:41], v[84:85]
	v_pk_mul_f32 v[36:37], v[36:37], v[88:89]
	v_pk_mul_f32 v[46:47], v[46:47], v[82:83]
	v_pk_mul_f32 v[42:43], v[42:43], v[86:87]
	v_pk_mul_f32 v[38:39], v[38:39], v[90:91]
	v_pk_mul_f32 v[34:35], v[34:35], v[94:95]
	v_pk_mul_f32 v[32:33], v[32:33], v[92:93]

; #define MFMA32(a, b, c) __builtin_amdgcn_mfma_f32_32x32x16_bf16((a), (b), (c), 0, 0, 0)
; #define SBAR() __builtin_amdgcn_sched_barrier(0)
; DI void qkt(f32x16& p0, f32x16& p1, const char* Ks, const bf16x8* qr, float negm, int r32, int hi) {
; #pragma unroll
;     for (int i = 0; i < 16; ++i) { p0[i] = negm; p1[i] = negm; }
; #pragma unroll
;     for (int d0 = 0; d0 < 8; ++d0) { const int cb = (d0 * 16 + hi * 8) * 2;
;         bf16x8 b0 = *(const bf16x8*)(Ks + KSWZ(r32, cb));
;         bf16x8 b1 = *(const bf16x8*)(Ks + KSWZ(32 + r32, cb));
;         p0 = MFMA32(b0, qr[d0], p0);
;         p1 = MFMA32(b1, qr[d0], p1); }
; }
; DI void attn_unit(const bf16_t* __restrict__ Qb, const bf16_t* __restrict__ Kh, const bf16_t* __restrict__ Vh, bf16_t* __restrict__ Ob, const float* __restrict__ onw, int seq, char* lds) {
;     ...
;     SBAR(); qkt(pB0, pB1, K_lds + SHM_K, qr, -m_reg, r32, hi);
;     finishSM(pA0, pA1, alA, l_reg, pa0, pa1, pa2, pa3); SBAR();
;     { const float pm = pv_d0_sm(o, vb0, pa0, pa1, pa2, pa3, pB0, pB1); smB<false>(pB0, pB1, pm, m_reg, alB); }
.LBB0_595:
	s_add_u32 m0, s100, 0x4000
	s_nop 0
	global_load_lds_dwordx4 v248, s[98:99]
	s_add_u32 m0, s100, 0x6000
	s_nop 0
	global_load_lds_dwordx4 v249, s[98:99]
	ds_read_b128 v[204:207], v183 offset:49152
	ds_read_b128 v[216:219], v183 offset:57344
	v_xor_b32_e32 v80, 0x80000000, v215
	v_mov_b32_e32 v81, v80
	v_mov_b32_e32 v82, v80
	v_mov_b32_e32 v83, v80
	v_mov_b32_e32 v84, v80
	v_mov_b32_e32 v85, v80
	v_mov_b32_e32 v86, v80
	v_mov_b32_e32 v87, v80
	v_mov_b32_e32 v88, v80
	v_mov_b32_e32 v89, v80
	v_mov_b32_e32 v90, v80
	v_mov_b32_e32 v91, v80
	v_mov_b32_e32 v92, v80
	v_mov_b32_e32 v93, v80
	v_mov_b32_e32 v94, v80
	v_mov_b32_e32 v95, v80
	v_exp_f32_e32 v145, v65
	v_add_f32_e32 v65, 0, v166
	s_waitcnt lgkmcnt(1)
	v_mfma_f32_32x32x16_bf16 v[96:111], v[204:207], v[140:143], v[80:95]
	v_add_f32_e32 v65, v167, v65
	v_add_f32_e32 v65, v162, v65
	v_add_f32_e32 v65, v163, v65
	v_add_f32_e32 v65, v158, v65
	v_add_f32_e32 v65, v159, v65
	v_add_f32_e32 v65, v156, v65
	v_add_f32_e32 v65, v157, v65
	s_waitcnt lgkmcnt(0)
	v_mfma_f32_32x32x16_bf16 v[80:95], v[216:219], v[140:143], v[80:95]
	ds_read_b128 v[140:143], v208 offset:49152
	ds_read_b128 v[204:207], v208 offset:57344
	v_add_f32_e32 v65, v168, v65
	v_add_f32_e32 v65, v169, v65
	v_add_f32_e32 v65, v164, v65
	v_add_f32_e32 v65, v165, v65
	v_exp_f32_e32 v64, v64
	v_add_f32_e32 v65, v160, v65
	s_waitcnt lgkmcnt(1)
	v_mfma_f32_32x32x16_bf16 v[96:111], v[140:143], v[136:139], v[96:111]
	ds_read_b128 v[140:143], v209 offset:49152
	ds_read_b128 v[216:219], v209 offset:57344
	v_add_f32_e32 v65, v161, v65
	v_exp_f32_e32 v66, v66
	v_add_f32_e32 v65, v146, v65
	v_exp_f32_e32 v67, v67
	v_add_f32_e32 v65, v147, v65
	v_exp_f32_e32 v68, v68
	s_waitcnt lgkmcnt(2)
	v_mfma_f32_32x32x16_bf16 v[80:95], v[204:207], v[136:139], v[80:95]
	ds_read_b128 v[136:139], v210 offset:49152
	ds_read_b128 v[204:207], v210 offset:57344
	ds_read_b128 v[220:223], v211 offset:49152
	ds_read_b128 v[208:211], v211 offset:57344
	ds_read_b128 v[224:227], v212 offset:49152
	ds_read_b128 v[228:231], v212 offset:57344
	ds_read_b128 v[232:235], v213 offset:49152
	ds_read_b128 v[236:239], v213 offset:57344
	v_add_f32_e32 v65, v64, v65
	v_exp_f32_e32 v69, v69
	v_add_f32_e32 v65, v145, v65
	v_exp_f32_e32 v70, v70
	v_add_f32_e32 v65, v66, v65
	v_exp_f32_e32 v71, v71
	s_waitcnt lgkmcnt(9)
	v_mfma_f32_32x32x16_bf16 v[96:111], v[140:143], v[132:135], v[96:111]
	v_add_f32_e32 v65, v67, v65
	v_exp_f32_e32 v72, v72
	v_add_f32_e32 v65, v68, v65
	ds_read_b128 v[140:143], v214 offset:49152
	ds_read_b128 v[212:215], v214 offset:57344
	v_exp_f32_e32 v73, v73
	v_add_f32_e32 v65, v69, v65
	v_add_f32_e32 v65, v70, v65
	s_waitcnt lgkmcnt(10)
	v_mfma_f32_32x32x16_bf16 v[80:95], v[216:219], v[132:135], v[80:95]
	v_exp_f32_e32 v132, v74
	v_exp_f32_e32 v133, v75
	v_add_f32_e32 v65, v71, v65
	v_exp_f32_e32 v134, v76
	v_add_f32_e32 v65, v72, v65
	v_exp_f32_e32 v135, v77
	v_add_f32_e32 v65, v73, v65
	s_waitcnt lgkmcnt(9)
	v_mfma_f32_32x32x16_bf16 v[96:111], v[136:139], v[128:131], v[96:111]
	v_exp_f32_e32 v78, v78
	v_add_f32_e32 v65, v132, v65
	v_exp_f32_e32 v79, v79
	v_add_f32_e32 v65, v133, v65
	v_add_f32_e32 v65, v134, v65
	v_add_f32_e32 v65, v135, v65
	v_add_f32_e32 v65, v78, v65
	s_waitcnt lgkmcnt(8)
	v_mfma_f32_32x32x16_bf16 v[80:95], v[204:207], v[128:131], v[80:95]
	v_add_f32_e32 v65, v79, v65
	v_cvt_pk_bf16_f32 v74, v166, v167
	v_cvt_pk_bf16_f32 v75, v162, v163
	v_cvt_pk_bf16_f32 v76, v158, v159
	v_cvt_pk_bf16_f32 v77, v156, v157
	s_nop 0
	v_permlane32_swap_b32_e32 v74, v76
	s_waitcnt lgkmcnt(7)
	v_mfma_f32_32x32x16_bf16 v[96:111], v[220:223], v[124:127], v[96:111]
	v_permlane32_swap_b32_e32 v75, v77
	s_waitcnt lgkmcnt(6)
	v_mfma_f32_32x32x16_bf16 v[80:95], v[208:211], v[124:127], v[80:95]
	s_waitcnt lgkmcnt(5)
	v_mfma_f32_32x32x16_bf16 v[96:111], v[224:227], v[120:123], v[96:111]
	s_waitcnt lgkmcnt(4)
	v_mfma_f32_32x32x16_bf16 v[80:95], v[228:231], v[120:123], v[80:95]
	v_mov_b32_e32 v120, v65
	s_nop 1
	v_permlane32_swap_b32_e32 v65, v120
	v_cvt_pk_bf16_f32 v122, v168, v169
	v_cvt_pk_bf16_f32 v123, v164, v165
	v_cvt_pk_bf16_f32 v124, v160, v161
	v_cvt_pk_bf16_f32 v125, v146, v147
	s_waitcnt lgkmcnt(3)
	v_mfma_f32_32x32x16_bf16 v[96:111], v[232:235], v[116:119], v[96:111]
	v_permlane32_swap_b32_e32 v122, v124
	v_permlane32_swap_b32_e32 v123, v125
	s_waitcnt lgkmcnt(2)
	v_mfma_f32_32x32x16_bf16 v[80:95], v[236:239], v[116:119], v[80:95]
	v_cvt_pk_bf16_f32 v116, v64, v145
	v_cvt_pk_bf16_f32 v117, v66, v67
	v_cvt_pk_bf16_f32 v118, v68, v69
	v_cvt_pk_bf16_f32 v119, v70, v71
	v_cvt_pk_bf16_f32 v126, v72, v73
	v_cvt_pk_bf16_f32 v127, v132, v133
	v_cvt_pk_bf16_f32 v128, v134, v135
	s_waitcnt lgkmcnt(1)
	v_mfma_f32_32x32x16_bf16 v[96:111], v[140:143], v[112:115], v[96:111]
	v_cvt_pk_bf16_f32 v129, v78, v79
	v_permlane32_swap_b32_e32 v116, v118
	v_permlane32_swap_b32_e32 v117, v119
	v_permlane32_swap_b32_e32 v126, v128
	s_waitcnt lgkmcnt(0)
	v_mfma_f32_32x32x16_bf16 v[80:95], v[212:215], v[112:115], v[80:95]
	v_permlane32_swap_b32_e32 v127, v129
	ds_read_b64_tr_b16 v[66:67], v175 offset:0
	ds_read_b64_tr_b16 v[68:69], v175 offset:0x800
	ds_read_b64_tr_b16 v[70:71], v175 offset:0x1000
	ds_read_b64_tr_b16 v[72:73], v175 offset:0x1800
	ds_read_b64_tr_b16 v[112:113], v175 offset:0x2000
	ds_read_b64_tr_b16 v[114:115], v175 offset:0x2800
	ds_read_b64_tr_b16 v[130:131], v175 offset:0x3000
	ds_read_b64_tr_b16 v[132:133], v175 offset:0x3800
	s_waitcnt lgkmcnt(0)
; #define SBAR() __builtin_amdgcn_sched_barrier(0)
; #define RESC(a) do { if (__any((a) < 1.f)) { if (hi == 0) al_l[r32] = (a); asm volatile("s_waitcnt lgkmcnt(0)" ::: "memory"); \
;     _Pragma("unroll") for (int d = 0; d < 4; ++d) _Pragma("unroll") for (int r = 0; r < 16; ++r) o[d][r] *= al_l[crow(r, hi)]; } } while (0)
; DI void attn_unit(const bf16_t* __restrict__ Qb, const bf16_t* __restrict__ Kh, const bf16_t* __restrict__ Vh, bf16_t* __restrict__ Ob, const float* __restrict__ onw, int seq, char* lds) {
;     ...
;     SBAR(); qkt(pB0, pB1, K_lds + SHM_K, qr, -m_reg, r32, hi);
;     finishSM(pA0, pA1, alA, l_reg, pa0, pa1, pa2, pa3); SBAR();
;     { const float pm = pv_d0_sm(o, vb0, pa0, pa1, pa2, pa3, pB0, pB1); smB<false>(pB0, pB1, pm, m_reg, alB); }
;     __syncthreads(); RESC(alB);
;     finishSM(pB0, pB1, alB, l_reg, pa0, pa1, pa2, pa3); SBAR();
;     pv_d0(o, vb0 + (int)SHM_V, pa0, pa1, pa2, pa3);
	s_nop 0
	v_mfma_f32_32x32x16_bf16 v[0:15], v[74:77], v[66:69], v[0:15]
	s_nop 3
	v_max_f32_e32 v64, v97, v97
	v_max_f32_e32 v66, v96, v96
	v_max_f32_e32 v64, v66, v64
	ds_read_b64_tr_b16 v[66:67], v175 offset:0x200
	ds_read_b64_tr_b16 v[68:69], v175 offset:0xa00
	v_max3_f32 v64, v64, v98, v99
	v_max3_f32 v64, v64, v100, v101
	v_mfma_f32_32x32x16_bf16 v[0:15], v[122:125], v[70:73], v[0:15]
	ds_read_b64_tr_b16 v[70:71], v175 offset:0x1200
	ds_read_b64_tr_b16 v[72:73], v175 offset:0x1a00
	ds_read_b64_tr_b16 v[134:135], v175 offset:0x2200
	ds_read_b64_tr_b16 v[136:137], v175 offset:0x2a00
	v_max3_f32 v64, v64, v102, v103
	ds_read_b64_tr_b16 v[138:139], v175 offset:0x3200
	v_max3_f32 v64, v64, v104, v105
	v_mfma_f32_32x32x16_bf16 v[0:15], v[116:119], v[112:115], v[0:15]
	ds_read_b64_tr_b16 v[140:141], v175 offset:0x3a00
	v_max3_f32 v64, v64, v106, v107
	s_waitcnt lgkmcnt(0)
	v_max3_f32 v64, v64, v108, v109
	v_max3_f32 v64, v64, v110, v111
	v_mfma_f32_32x32x16_bf16 v[0:15], v[126:129], v[130:133], v[0:15]
	v_mfma_f32_32x32x16_bf16 v[48:63], v[74:77], v[66:69], v[48:63]
	v_max3_f32 v64, v64, v80, v81
	v_max3_f32 v64, v64, v82, v83
	v_max3_f32 v64, v64, v84, v85
	v_max3_f32 v64, v64, v86, v87
	v_max3_f32 v64, v64, v88, v89
	v_max3_f32 v64, v64, v90, v91
	v_max3_f32 v64, v64, v92, v93
	v_mfma_f32_32x32x16_bf16 v[48:63], v[122:125], v[70:73], v[48:63]
	v_max3_f32 v64, v64, v94, v95
	v_mov_b32_e32 v66, v64
	s_nop 1
	v_permlane32_swap_b32_e32 v64, v66
	v_max_f32_e32 v66, v66, v66
	v_max_f32_e32 v64, v64, v64
	v_max_f32_e32 v112, v64, v66
	v_mfma_f32_32x32x16_bf16 v[48:63], v[116:119], v[134:137], v[48:63]
	ds_read_b64_tr_b16 v[66:67], v175 offset:0x400
	ds_read_b64_tr_b16 v[68:69], v175 offset:0xc00
	ds_read_b64_tr_b16 v[130:131], v175 offset:0x1400
	ds_read_b64_tr_b16 v[132:133], v175 offset:0x1c00
	ds_read_b64_tr_b16 v[134:135], v175 offset:0x2400
	ds_read_b64_tr_b16 v[136:137], v175 offset:0x2c00
	ds_read_b64_tr_b16 v[156:157], v175 offset:0x3400
	v_mfma_f32_32x32x16_bf16 v[48:63], v[126:129], v[138:141], v[48:63]
	ds_read_b64_tr_b16 v[158:159], v175 offset:0x3c00
	s_waitcnt lgkmcnt(0)
	v_mfma_f32_32x32x16_bf16 v[16:31], v[74:77], v[66:69], v[16:31]
	v_exp_f32_e32 v70, v96
	v_exp_f32_e32 v71, v97
	ds_read_b64_tr_b16 v[96:97], v175 offset:0x600
	v_exp_f32_e32 v72, v98
	v_exp_f32_e32 v73, v99
	ds_read_b64_tr_b16 v[98:99], v175 offset:0xe00
	v_exp_f32_e32 v68, v100
	v_mfma_f32_32x32x16_bf16 v[16:31], v[122:125], v[130:133], v[16:31]
	v_exp_f32_e32 v69, v101
	ds_read_b64_tr_b16 v[100:101], v175 offset:0x1600
	v_exp_f32_e32 v66, v102
	v_exp_f32_e32 v67, v103
	ds_read_b64_tr_b16 v[102:103], v175 offset:0x1e00
	ds_read_b64_tr_b16 v[130:131], v175 offset:0x2600
	ds_read_b64_tr_b16 v[132:133], v175 offset:0x2e00
	v_mfma_f32_32x32x16_bf16 v[16:31], v[116:119], v[134:137], v[16:31]
	ds_read_b64_tr_b16 v[134:135], v175 offset:0x3600
	ds_read_b64_tr_b16 v[136:137], v175 offset:0x3e00
	s_waitcnt lgkmcnt(0)
	v_mfma_f32_32x32x16_bf16 v[16:31], v[126:129], v[156:159], v[16:31]
	v_mfma_f32_32x32x16_bf16 v[32:47], v[74:77], v[96:99], v[32:47]
	v_exp_f32_e32 v96, v104
	v_exp_f32_e32 v97, v105
	v_exp_f32_e32 v76, v106
	v_exp_f32_e32 v77, v107
	v_exp_f32_e32 v78, v108
	v_exp_f32_e32 v79, v109
	v_exp_f32_e32 v74, v110
	v_mfma_f32_32x32x16_bf16 v[32:47], v[122:125], v[100:103], v[32:47]
	v_exp_f32_e32 v75, v111
	v_cmp_ge_f32_e32 vcc, s82, v112
	v_mov_b32_e32 v64, 1.0
	s_cmp_eq_u64 vcc, exec
	v_mfma_f32_32x32x16_bf16 v[32:47], v[116:119], v[130:133], v[32:47]
	v_mfma_f32_32x32x16_bf16 v[32:47], v[126:129], v[134:137], v[32:47]
	s_cbranch_scc0 .LBB0_638
.LBB0_596:
	v_cmp_gt_f32_e32 vcc, 1.0, v64
	s_waitcnt vmcnt(0)
	s_barrier
	s_cbranch_vccz .LBB0_600
	s_and_saveexec_b64 s[14:15], s[2:3]
	ds_write_b32 v172, v64 offset:128
	s_or_b64 exec, exec, s[14:15]
	s_waitcnt lgkmcnt(0)
	v_add_u32_e32 v110, v171, v184
	ds_read_b128 v[98:101], v110 offset:224
	ds_read_b128 v[102:105], v110 offset:192
	ds_read_b128 v[106:109], v110 offset:160
	ds_read_b128 v[110:113], v110 offset:128
	s_waitcnt lgkmcnt(3)
	v_pk_mul_f32 v[12:13], v[12:13], v[98:99]
	s_waitcnt lgkmcnt(2)
	v_pk_mul_f32 v[8:9], v[8:9], v[102:103]
	s_waitcnt lgkmcnt(1)
	v_pk_mul_f32 v[4:5], v[4:5], v[106:107]
	v_pk_mul_f32 v[14:15], v[14:15], v[100:101]
	v_pk_mul_f32 v[10:11], v[10:11], v[104:105]
	v_pk_mul_f32 v[6:7], v[6:7], v[108:109]
	s_waitcnt lgkmcnt(0)
	v_pk_mul_f32 v[2:3], v[2:3], v[112:113]
	v_pk_mul_f32 v[0:1], v[0:1], v[110:111]
	v_pk_mul_f32 v[60:61], v[60:61], v[98:99]
	v_pk_mul_f32 v[56:57], v[56:57], v[102:103]
	v_pk_mul_f32 v[52:53], v[52:53], v[106:107]
	v_pk_mul_f32 v[62:63], v[62:63], v[100:101]
	v_pk_mul_f32 v[58:59], v[58:59], v[104:105]
	v_pk_mul_f32 v[54:55], v[54:55], v[108:109]
	v_pk_mul_f32 v[50:51], v[50:51], v[112:113]
	v_pk_mul_f32 v[48:49], v[48:49], v[110:111]
	v_pk_mul_f32 v[28:29], v[28:29], v[98:99]
	v_pk_mul_f32 v[24:25], v[24:25], v[102:103]
	v_pk_mul_f32 v[20:21], v[20:21], v[106:107]
	v_pk_mul_f32 v[30:31], v[30:31], v[100:101]
	v_pk_mul_f32 v[26:27], v[26:27], v[104:105]
	v_pk_mul_f32 v[22:23], v[22:23], v[108:109]
	v_pk_mul_f32 v[18:19], v[18:19], v[112:113]
	v_pk_mul_f32 v[16:17], v[16:17], v[110:111]
	v_pk_mul_f32 v[44:45], v[44:45], v[98:99]
	v_pk_mul_f32 v[40:41], v[40:41], v[102:103]
	v_pk_mul_f32 v[36:37], v[36:37], v[106:107]
	v_pk_mul_f32 v[46:47], v[46:47], v[100:101]
	v_pk_mul_f32 v[42:43], v[42:43], v[104:105]
	v_pk_mul_f32 v[38:39], v[38:39], v[108:109]
	v_pk_mul_f32 v[34:35], v[34:35], v[112:113]
	v_pk_mul_f32 v[32:33], v[32:33], v[110:111]
